# o16 + MIX1 queue order: light indexer items (index >= 128) moved behind the GDN chunk items (LPT order)
# baseline (speedup 1.0000x reference)
.LBB0_1229:
	s_or_b64 exec, exec, s[0:1]
	s_waitcnt lgkmcnt(0)
	s_barrier
	ds_read_b32 v1, v155
	s_movk_i32 s0, 0x8af
	s_waitcnt lgkmcnt(0)
	v_cmp_lt_u32_e32 vcc, s0, v1
	v_readfirstlane_b32 s42, v1
	s_mov_b64 s[0:1], -1
	s_cbranch_vccnz .LBB0_1224
	s_cmpk_gt_u32 s42, 0x2ff
	s_cbranch_scc1 .Lq_nomap
	s_cmpk_lt_u32 s42, 0x80
	s_cbranch_scc1 .Lq_nomap
	s_cmpk_lt_u32 s42, 0x280
	s_cbranch_scc1 .Lq_g1
	s_sub_u32 s42, s42, 0x200
	s_branch .Lq_nomap
.Lq_g1:
	s_add_u32 s42, s42, 0x80
.Lq_nomap:
	s_cmpk_gt_u32 s42, 0xff
	s_cbranch_scc0 .LBB0_1402
	s_cmpk_gt_u32 s42, 0x2ff
	s_cbranch_scc0 .LBB0_1300
	s_cmpk_gt_u32 s42, 0x407
	s_cbranch_scc0 .LBB0_1274
	s_cmpk_gt_u32 s42, 0x40f
	s_cbranch_scc0 .LBB0_1271
	v_lshl_add_u32 v1, s42, 3, v131
	s_movk_i32 s0, 0x2500
	v_cmp_gt_i32_e32 vcc, s0, v1
	s_and_saveexec_b64 s[0:1], vcc
	s_xor_b64 s[2:3], exec, s[0:1]
	s_cbranch_execz .LBB0_1270
	s_movk_i32 s0, 0x2100
	v_lshlrev_b32_e32 v2, 6, v1
	v_cmp_gt_i32_e32 vcc, s0, v1
	s_and_saveexec_b64 s[0:1], vcc
	s_xor_b64 s[4:5], exec, s[0:1]
	s_cbranch_execz .LBB0_1267
	s_movk_i32 s0, 0x15ff
	v_cmp_lt_i32_e32 vcc, s0, v1
	s_and_saveexec_b64 s[0:1], vcc
	s_xor_b64 s[0:1], exec, s[0:1]
	s_cbranch_execz .LBB0_1238
	v_lshlrev_b32_e32 v1, 1, v1
	v_and_b32_e32 v1, 0x7fffffc0, v1
	v_add_u32_e32 v66, 0xffffd400, v1
	v_or_b32_e32 v134, v66, v132
	v_readlane_b32 s8, v253, 40
	v_and_b32_e32 v68, 0x7c0, v2
	v_lshlrev_b64 v[2:3], 13, v[134:135]
	v_readlane_b32 s22, v253, 54
	v_readlane_b32 s23, v253, 55
	v_lshlrev_b32_e32 v134, 2, v68
	v_mov_b32_e32 v145, v135
	v_lshl_add_u64 v[2:3], s[22:23], 0, v[2:3]
	v_lshl_add_u64 v[2:3], v[2:3], 0, v[134:135]
	s_waitcnt vmcnt(9)
	v_lshl_add_u64 v[58:59], v[2:3], 0, v[144:145]
	s_movk_i32 s8, 0x2000
	v_add_co_u32_e32 v6, vcc, s8, v58
	s_movk_i32 s6, 0x4000
	s_nop 0
	v_addc_co_u32_e32 v7, vcc, 0, v59, vcc
	v_add_co_u32_e32 v10, vcc, s6, v58
	s_movk_i32 s6, 0x6000
	s_nop 0
	v_addc_co_u32_e32 v11, vcc, 0, v59, vcc
	v_add_co_u32_e32 v14, vcc, s6, v58
	s_mov_b32 s6, 0x8000
	s_nop 0
	v_addc_co_u32_e32 v15, vcc, 0, v59, vcc
	v_add_co_u32_e32 v18, vcc, s6, v58
	s_mov_b32 s6, 0xa000
	s_nop 0
	v_addc_co_u32_e32 v19, vcc, 0, v59, vcc
	v_add_co_u32_e32 v22, vcc, s6, v58
	s_mov_b32 s6, 0xc000
	s_nop 0
	v_addc_co_u32_e32 v23, vcc, 0, v59, vcc
	v_add_co_u32_e32 v26, vcc, s6, v58
	s_mov_b32 s6, 0xe000
	s_nop 0
	v_addc_co_u32_e32 v27, vcc, 0, v59, vcc
	v_add_co_u32_e32 v30, vcc, s6, v58
	s_mov_b32 s6, 0x10000
	s_nop 0
	v_addc_co_u32_e32 v31, vcc, 0, v59, vcc
	v_add_co_u32_e32 v34, vcc, s6, v58
	s_mov_b32 s6, 0x12000
	s_nop 0
	v_addc_co_u32_e32 v35, vcc, 0, v59, vcc
	v_add_co_u32_e32 v38, vcc, s6, v58
	s_mov_b32 s6, 0x14000
	s_nop 0
	v_addc_co_u32_e32 v39, vcc, 0, v59, vcc
	v_add_co_u32_e32 v42, vcc, s6, v58
	s_mov_b32 s6, 0x16000
	s_nop 0
	v_addc_co_u32_e32 v43, vcc, 0, v59, vcc
	v_add_co_u32_e32 v46, vcc, s6, v58
	s_mov_b32 s6, 0x18000
	s_nop 0
	v_addc_co_u32_e32 v47, vcc, 0, v59, vcc
	v_add_co_u32_e32 v50, vcc, s6, v58
	s_mov_b32 s6, 0x1a000
	s_nop 0
	v_addc_co_u32_e32 v51, vcc, 0, v59, vcc
	v_add_co_u32_e32 v54, vcc, s6, v58
	s_mov_b32 s6, 0x1c000
	s_nop 0
	v_addc_co_u32_e32 v55, vcc, 0, v59, vcc
	v_add_co_u32_e32 v60, vcc, s6, v58
	s_mov_b32 s6, 0x1e000
	s_nop 0
	v_addc_co_u32_e32 v61, vcc, 0, v59, vcc
	s_waitcnt vmcnt(8)
	v_add_co_u32_e32 v62, vcc, s6, v58
	global_load_dwordx4 v[2:5], v[58:59], off nt
	s_nop 0
	global_load_dwordx4 v[6:9], v[6:7], off nt
	s_nop 0
	global_load_dwordx4 v[10:13], v[10:11], off nt
	s_nop 0
	global_load_dwordx4 v[14:17], v[14:15], off nt
	s_nop 0
	global_load_dwordx4 v[18:21], v[18:19], off nt
	s_nop 0
	global_load_dwordx4 v[22:25], v[22:23], off nt
	s_nop 0
	global_load_dwordx4 v[26:29], v[26:27], off nt
	s_nop 0
	global_load_dwordx4 v[30:33], v[30:31], off nt
	v_addc_co_u32_e32 v63, vcc, 0, v59, vcc
	global_load_dwordx4 v[34:37], v[34:35], off nt
	s_nop 0
	global_load_dwordx4 v[38:41], v[38:39], off nt
	s_nop 0
	global_load_dwordx4 v[42:45], v[42:43], off nt
	s_nop 0
	global_load_dwordx4 v[46:49], v[46:47], off nt
	s_nop 0
	global_load_dwordx4 v[50:53], v[50:51], off nt
	s_nop 0
	global_load_dwordx4 v[54:57], v[54:55], off nt
	s_nop 0
	global_load_dwordx4 v[58:61], v[60:61], off nt
	s_nop 0
	global_load_dwordx4 v[62:65], v[62:63], off nt
	v_or_b32_e32 v1, v68, v130
	v_mul_u32_u24_e32 v1, 0x1600, v1
	v_readlane_b32 s6, v254, 30
	v_lshlrev_b32_e32 v134, 1, v1
	v_readlane_b32 s7, v254, 31
	v_mov_b32_e32 v67, v135
	v_mov_b32_e32 v147, v135
	v_lshl_add_u64 v[68:69], s[6:7], 0, v[134:135]
	v_lshl_add_u64 v[66:67], v[66:67], 1, v[68:69]
	v_lshl_add_u64 v[74:75], v[66:67], 0, v[146:147]
	s_movk_i32 s6, 0x5000
	v_readlane_b32 s9, v253, 41
	v_readlane_b32 s10, v253, 42
	v_readlane_b32 s11, v253, 43
	v_readlane_b32 s12, v253, 44
	v_readlane_b32 s13, v253, 45
	v_readlane_b32 s14, v253, 46
	v_readlane_b32 s15, v253, 47
	v_readlane_b32 s16, v253, 48
	v_readlane_b32 s17, v253, 49
	v_readlane_b32 s18, v253, 50
	v_readlane_b32 s19, v253, 51
	v_readlane_b32 s20, v253, 52
	v_readlane_b32 s21, v253, 53
	s_waitcnt vmcnt(14)
	v_cvt_pk_bf16_f32 v66, v2, v6
	s_waitcnt vmcnt(12)
	v_cvt_pk_bf16_f32 v67, v10, v14
	s_waitcnt vmcnt(10)
	v_cvt_pk_bf16_f32 v68, v18, v22
	s_waitcnt vmcnt(8)
	v_cvt_pk_bf16_f32 v69, v26, v30
	v_add_co_u32_e32 v2, vcc, s8, v74
	s_waitcnt vmcnt(6)
	v_cvt_pk_bf16_f32 v70, v34, v38
	s_waitcnt vmcnt(4)
	v_cvt_pk_bf16_f32 v71, v42, v46
	s_waitcnt vmcnt(2)
	v_cvt_pk_bf16_f32 v72, v50, v54
	s_waitcnt vmcnt(0)
	v_cvt_pk_bf16_f32 v73, v58, v62
	global_store_dwordx4 v[74:75], v[66:69], off
	global_store_dwordx4 v[74:75], v[70:73], off offset:16
	v_cvt_pk_bf16_f32 v6, v37, v41
	v_cvt_pk_bf16_f32 v66, v3, v7
	v_cvt_pk_bf16_f32 v67, v11, v15
	v_cvt_pk_bf16_f32 v68, v19, v23
	v_cvt_pk_bf16_f32 v69, v27, v31
	v_addc_co_u32_e32 v3, vcc, 0, v75, vcc
	v_cvt_pk_bf16_f32 v70, v35, v39
	v_cvt_pk_bf16_f32 v71, v43, v47
	v_cvt_pk_bf16_f32 v72, v51, v55
	v_cvt_pk_bf16_f32 v73, v59, v63
	global_store_dwordx4 v[2:3], v[66:69], off offset:3072
	global_store_dwordx4 v[2:3], v[70:73], off offset:3088
	v_add_co_u32_e32 v2, vcc, s6, v74
	v_cvt_pk_bf16_f32 v66, v4, v8
	s_nop 0
	v_addc_co_u32_e32 v3, vcc, 0, v75, vcc
	v_cvt_pk_bf16_f32 v67, v12, v16
	v_cvt_pk_bf16_f32 v68, v20, v24
	v_cvt_pk_bf16_f32 v69, v28, v32
	v_add_co_u32_e32 v10, vcc, 0x8000, v74
	v_cvt_pk_bf16_f32 v70, v36, v40
	v_cvt_pk_bf16_f32 v71, v44, v48
	v_cvt_pk_bf16_f32 v72, v52, v56
	v_cvt_pk_bf16_f32 v73, v60, v64
	global_store_dwordx4 v[2:3], v[66:69], off offset:2048
	global_store_dwordx4 v[2:3], v[70:73], off offset:2064
	v_cvt_pk_bf16_f32 v2, v5, v9
	v_cvt_pk_bf16_f32 v3, v13, v17
	v_cvt_pk_bf16_f32 v4, v21, v25
	v_cvt_pk_bf16_f32 v5, v29, v33
	v_addc_co_u32_e32 v11, vcc, 0, v75, vcc
	v_cvt_pk_bf16_f32 v7, v45, v49
	v_cvt_pk_bf16_f32 v8, v53, v57
	v_cvt_pk_bf16_f32 v9, v61, v65
	global_store_dwordx4 v[10:11], v[2:5], off offset:1024
	global_store_dwordx4 v[10:11], v[6:9], off offset:1040
